# grid barrier leader signals per-XCD generation before its own L1 invalidate; hyena conv invalid blocks read a zeroed LDS block instead of masking data
# speedup vs baseline: 1.0360x; 1.0022x over previous
.LBB0_509:
	s_or_b64 exec, exec, s[6:7]
	s_mov_b64 s[6:7], exec
	v_mbcnt_lo_u32_b32 v0, s6, 0
	v_mbcnt_hi_u32_b32 v0, s7, v0
	v_cmp_eq_u32_e32 vcc, 0, v0
	s_waitcnt vmcnt(0)
	s_and_saveexec_b64 s[8:9], vcc
	s_cbranch_execz .LBB0_511
	s_bcnt1_i32_b64 s4, s[6:7]
	v_mov_b32_e32 v1, s4
	v_readlane_b32 s4, v254, 15
	v_mov_b32_e32 v0, 0
	v_readlane_b32 s5, v254, 16
	s_nop 4
	global_atomic_add v0, v1, s[4:5]
.LBB0_511:
	s_or_b64 exec, exec, s[8:9]
	buffer_inv sc1
	s_waitcnt vmcnt(0)

.LBB0_604:
	s_or_b64 exec, exec, s[2:3]
	s_mov_b64 s[2:3], exec
	v_mbcnt_lo_u32_b32 v0, s2, 0
	v_mbcnt_hi_u32_b32 v0, s3, v0
	v_cmp_eq_u32_e32 vcc, 0, v0
	s_waitcnt vmcnt(0)
	s_and_saveexec_b64 s[8:9], vcc
	s_cbranch_execz .LBB0_606
	s_bcnt1_i32_b64 s2, s[2:3]
	v_mov_b32_e32 v0, s2
	v_readlane_b32 s2, v254, 15
	v_readlane_b32 s3, v254, 16
	s_nop 4
	global_atomic_add v65, v0, s[2:3]

.LBB0_704:
	s_or_b64 exec, exec, s[18:19]
	v_lshlrev_b32_e32 v221, 2, v176
	v_add_u32_e32 v221, 0x11040, v221
	ds_write_b32 v221, v65
	s_xor_b64 s[70:71], s[8:9], -1
	s_lshl_b64 s[4:5], s[10:11], 2
	s_add_u32 s4, s82, s4
	s_addc_u32 s5, s83, s5
	s_waitcnt lgkmcnt(0)
	s_barrier
	global_load_dword v72, v65, s[4:5]
	v_mov_b32_e32 v0, 0
	s_mov_b64 s[10:11], 0
	v_mov_b32_e32 v32, v169
	v_mov_b32_e32 v33, v168
	v_mov_b32_e32 v34, v167
	v_mov_b32_e32 v35, v166
	v_mov_b32_e32 v1, v0
	v_mov_b32_e32 v2, v0
	v_mov_b32_e32 v3, v0
	v_mov_b32_e32 v4, v0
	v_mov_b32_e32 v5, v0
	v_mov_b32_e32 v6, v0
	v_mov_b32_e32 v7, v0
	v_mov_b32_e32 v8, v0
	v_mov_b32_e32 v9, v0
	v_mov_b32_e32 v10, v0
	v_mov_b32_e32 v11, v0
	v_mov_b32_e32 v12, v0
	v_mov_b32_e32 v13, v0
	v_mov_b32_e32 v14, v0
	v_mov_b32_e32 v15, v0
.LBB0_705:
	v_mov_b32_e32 v221, 0x11040
	v_cmp_gt_u32_e32 vcc, s73, v32
	v_lshl_add_u32 v220, v33, 1, v121
	s_nop 1
	v_cndmask_b32_e32 v220, v221, v220, vcc
	ds_read2_b32 v[36:37], v34 offset1:1
	ds_read2_b32 v[38:39], v34 offset0:2 offset1:3
	ds_read_b128 v[40:43], v220
	ds_read_b128 v[44:47], v220 offset:32
	ds_read2_b32 v[200:201], v34 offset0:8 offset1:9
	ds_read2_b32 v[202:203], v34 offset0:10 offset1:11
.Lconv_loop:
	v_add_u32_e32 v35, 1, v35
	v_add_u32_e32 v32, -1, v32
	v_cmp_gt_u32_e32 vcc, s73, v32
	v_subrev_u32_e32 v33, 40, v33
	v_subrev_u32_e32 v34, 64, v34
	v_lshl_add_u32 v220, v33, 1, v121
	v_cndmask_b32_e32 v220, v221, v220, vcc
	ds_read2_b32 v[204:205], v34 offset1:1
	ds_read2_b32 v[206:207], v34 offset0:2 offset1:3
	ds_read_b128 v[208:211], v220
	ds_read_b128 v[212:215], v220 offset:32
	ds_read2_b32 v[216:217], v34 offset0:8 offset1:9
	ds_read2_b32 v[218:219], v34 offset0:10 offset1:11
	s_waitcnt lgkmcnt(6)
	v_mfma_f32_32x32x16_bf16 v[0:15], v[36:39], v[40:43], v[0:15]
	v_mfma_f32_32x32x16_bf16 v[0:15], v[200:203], v[44:47], v[0:15]
	v_cmp_ge_i32_e32 vcc, v35, v61
	s_or_b64 s[10:11], vcc, s[10:11]
	s_andn2_b64 exec, exec, s[10:11]
	s_cbranch_execz .Lconv_exit
	v_add_u32_e32 v35, 1, v35
	v_add_u32_e32 v32, -1, v32
	v_cmp_gt_u32_e32 vcc, s73, v32
	v_subrev_u32_e32 v33, 40, v33
	v_subrev_u32_e32 v34, 64, v34
	v_lshl_add_u32 v220, v33, 1, v121
	v_cndmask_b32_e32 v220, v221, v220, vcc
	ds_read2_b32 v[36:37], v34 offset1:1
	ds_read2_b32 v[38:39], v34 offset0:2 offset1:3
	ds_read_b128 v[40:43], v220
	ds_read_b128 v[44:47], v220 offset:32
	ds_read2_b32 v[200:201], v34 offset0:8 offset1:9
	ds_read2_b32 v[202:203], v34 offset0:10 offset1:11
	s_waitcnt lgkmcnt(6)
	v_mfma_f32_32x32x16_bf16 v[0:15], v[204:207], v[208:211], v[0:15]
	v_mfma_f32_32x32x16_bf16 v[0:15], v[216:219], v[212:215], v[0:15]
	v_cmp_ge_i32_e32 vcc, v35, v61
	s_or_b64 s[10:11], vcc, s[10:11]
	s_andn2_b64 exec, exec, s[10:11]
	s_cbranch_execnz .Lconv_loop

.LBB0_1135:
	s_or_b64 exec, exec, s[8:9]
	s_mov_b64 s[8:9], exec
	v_mbcnt_lo_u32_b32 v0, s8, 0
	v_mbcnt_hi_u32_b32 v0, s9, v0
	v_cmp_eq_u32_e32 vcc, 0, v0
	s_waitcnt vmcnt(0)
	s_and_saveexec_b64 s[10:11], vcc
	s_cbranch_execz .LBB0_1137
	s_bcnt1_i32_b64 s2, s[8:9]
	v_mov_b32_e32 v0, s2
	v_readlane_b32 s2, v254, 15
	v_readlane_b32 s3, v254, 16
	s_nop 4
	global_atomic_add v65, v0, s[2:3]
.LBB0_1137:
	s_or_b64 exec, exec, s[10:11]
	buffer_inv sc1
	s_waitcnt vmcnt(0)
